# conv_mix loop unrolled x2 with both iterations loads in flight (on top of peel + plain SwiGLU stores)
# baseline (speedup 1.0000x reference)
.LBB0_287:
	s_andn2_b64 vcc, exec, s[8:9]
	s_cbranch_vccnz .LBB0_292
	s_and_saveexec_b64 s[8:9], s[36:37]
	v_readlane_b32 s36, v252, 17
	v_readlane_b32 s40, v252, 21
	v_readlane_b32 s41, v252, 22
	v_readlane_b32 s37, v252, 18
	v_readlane_b32 s38, v252, 19
	v_readlane_b32 s39, v252, 20
	v_readlane_b32 s42, v252, 23
	v_readlane_b32 s43, v252, 24
	v_readlane_b32 s44, v252, 25
	v_readlane_b32 s45, v252, 26
	v_readlane_b32 s46, v252, 27
	v_readlane_b32 s47, v252, 28
	v_readlane_b32 s48, v252, 29
	v_readlane_b32 s49, v252, 30
	v_readlane_b32 s50, v252, 31
	v_readlane_b32 s51, v252, 32
	s_cbranch_execz .LBB0_291
	s_mov_b64 s[12:13], s[40:41]
	v_lshlrev_b32_e32 v0, 3, v25
	s_lshl_b32 s6, s76, 3
	s_mov_b64 s[10:11], 0
	s_cmp_lg_u32 s76, 0x20000
	s_cbranch_scc1 .Lconv_orig
.LBB0_290:
	v_mul_hi_i32 v1, v25, s84
	v_lshrrev_b32_e32 v4, 31, v1
	v_ashrrev_i32_e32 v1, 4, v1
	v_mov_b64_e32 v[2:3], s[72:73]
	v_add_u32_e32 v4, v1, v4
	v_mad_i64_i32 v[2:3], s[0:1], v4, s85, v[2:3]
	v_add_u32_e32 v25, s76, v25
	v_and_b32_e32 v1, 0x1fff, v4
	s_movk_i32 s0, 0xfd00
	v_cmp_lt_i32_e32 vcc, s22, v25
	v_mad_u64_u32 v[6:7], s[0:1], v4, s0, v[0:1]
	s_or_b64 s[10:11], vcc, s[10:11]
	v_cmp_gt_u32_e32 vcc, 2, v1
	v_cmp_eq_u32_e64 s[0:1], 0, v1
	v_mov_b32_e32 v1, 0xffffe400
	v_ashrrev_i32_e32 v7, 31, v6
	v_cndmask_b32_e64 v22, v1, 0, vcc
	v_mov_b32_e32 v1, 0xfffff200
	v_cndmask_b32_e64 v39, -1, 0, s[0:1]
	v_lshl_add_u64 v[20:21], v[6:7], 2, s[12:13]
	v_cndmask_b32_e64 v38, v1, 0, s[0:1]
	v_cndmask_b32_e64 v46, 1.0, 0, s[0:1]
	s_mov_b64 s[0:1], 0x1800
	v_ashrrev_i32_e32 v5, 31, v4
	v_lshlrev_b64 v[18:19], 1, v[6:7]
	v_lshl_add_u64 v[34:35], v[20:21], 0, s[0:1]
	s_movk_i32 s0, 0x1000
	v_cndmask_b32_e64 v23, -1, 0, vcc
	v_lshlrev_b64 v[4:5], 11, v[4:5]
	v_cndmask_b32_e64 v24, 1.0, 0, vcc
	v_lshl_add_u64 v[40:41], v[2:3], 0, v[18:19]
	v_add_co_u32_e32 v30, vcc, s0, v20
	v_lshl_add_u64 v[26:27], s[66:67], 0, v[4:5]
	global_load_dwordx4 v[2:5], v[20:21], off offset:16
	global_load_dwordx4 v[6:9], v[20:21], off
	global_load_dwordx4 v[10:13], v[20:21], off offset:3088
	global_load_dwordx4 v[14:17], v[20:21], off offset:3072
	v_addc_co_u32_e32 v31, vcc, 0, v21, vcc
	v_lshl_add_u64 v[22:23], v[40:41], 0, v[22:23]
	v_lshl_add_u64 v[42:43], v[40:41], 0, v[38:39]
	v_lshl_add_u64 v[48:49], v[26:27], 0, v[18:19]
	global_load_dwordx4 v[18:21], v[40:41], off
	global_load_dwordx4 v[26:29], v[40:41], off offset:1536
	s_nop 0
	global_load_dwordx4 v[30:33], v[30:31], off offset:2048
	s_nop 0
	global_load_dwordx4 v[34:37], v[34:35], off offset:16
	s_nop 0
	global_load_dwordx4 v[38:41], v[22:23], off offset:1536
	s_nop 0
	global_load_dwordx4 v[42:45], v[42:43], off offset:1536
	v_add_u32_e32 v0, s6, v0
	v_mov_b32_e32 v64, v0
	v_mul_hi_i32 v65, v25, s84
	v_lshrrev_b32_e32 v68, 31, v65
	v_ashrrev_i32_e32 v65, 4, v65
	v_mov_b64_e32 v[66:67], s[72:73]
	v_add_u32_e32 v68, v65, v68
	v_mad_i64_i32 v[66:67], s[0:1], v68, s85, v[66:67]
	v_add_u32_e32 v25, s76, v25
	v_and_b32_e32 v65, 0x1fff, v68
	s_movk_i32 s0, 0xfd00
	v_cmp_lt_i32_e32 vcc, s22, v25
	v_mad_u64_u32 v[70:71], s[0:1], v68, s0, v[64:65]
	s_or_b64 s[10:11], vcc, s[10:11]
	v_cmp_gt_u32_e32 vcc, 2, v65
	v_cmp_eq_u32_e64 s[0:1], 0, v65
	v_mov_b32_e32 v65, 0xffffe400
	v_ashrrev_i32_e32 v71, 31, v70
	v_cndmask_b32_e64 v86, v65, 0, vcc
	v_mov_b32_e32 v65, 0xfffff200
	v_cndmask_b32_e64 v103, -1, 0, s[0:1]
	v_lshl_add_u64 v[84:85], v[70:71], 2, s[12:13]
	v_cndmask_b32_e64 v102, v65, 0, s[0:1]
	v_cndmask_b32_e64 v110, 1.0, 0, s[0:1]
	s_mov_b64 s[0:1], 0x1800
	v_ashrrev_i32_e32 v69, 31, v68
	v_lshlrev_b64 v[82:83], 1, v[70:71]
	v_lshl_add_u64 v[98:99], v[84:85], 0, s[0:1]
	s_movk_i32 s0, 0x1000
	v_cndmask_b32_e64 v87, -1, 0, vcc
	v_lshlrev_b64 v[68:69], 11, v[68:69]
	v_cndmask_b32_e64 v88, 1.0, 0, vcc
	v_lshl_add_u64 v[104:105], v[66:67], 0, v[82:83]
	v_add_co_u32_e32 v94, vcc, s0, v84
	v_lshl_add_u64 v[90:91], s[66:67], 0, v[68:69]
	global_load_dwordx4 v[66:69], v[84:85], off offset:16
	global_load_dwordx4 v[70:73], v[84:85], off
	global_load_dwordx4 v[74:77], v[84:85], off offset:3088
	global_load_dwordx4 v[78:81], v[84:85], off offset:3072
	v_addc_co_u32_e32 v95, vcc, 0, v85, vcc
	v_lshl_add_u64 v[86:87], v[104:105], 0, v[86:87]
	v_lshl_add_u64 v[106:107], v[104:105], 0, v[102:103]
	v_lshl_add_u64 v[112:113], v[90:91], 0, v[82:83]
	global_load_dwordx4 v[82:85], v[104:105], off
	global_load_dwordx4 v[90:93], v[104:105], off offset:1536
	s_nop 0
	global_load_dwordx4 v[94:97], v[94:95], off offset:2048
	s_nop 0
	global_load_dwordx4 v[98:101], v[98:99], off offset:16
	s_nop 0
	global_load_dwordx4 v[102:105], v[86:87], off offset:1536
	s_nop 0
	global_load_dwordx4 v[106:109], v[106:107], off offset:1536
	v_add_u32_e32 v0, s6, v0
	s_waitcnt vmcnt(10)
	v_pk_mul_f32 v[4:5], v[4:5], v[24:25] op_sel_hi:[1,0]
	v_pk_mul_f32 v[8:9], v[8:9], v[24:25] op_sel_hi:[1,0]
	v_pk_mul_f32 v[12:13], v[46:47], v[12:13] op_sel_hi:[0,1]
	v_pk_mul_f32 v[16:17], v[46:47], v[16:17] op_sel_hi:[0,1]
	v_pk_mul_f32 v[14:15], v[46:47], v[14:15] op_sel_hi:[0,1]
	v_pk_mul_f32 v[10:11], v[46:47], v[10:11] op_sel_hi:[0,1]
	v_pk_mul_f32 v[6:7], v[6:7], v[24:25] op_sel_hi:[1,0]
	v_pk_mul_f32 v[2:3], v[2:3], v[24:25] op_sel_hi:[1,0]
	v_lshlrev_b32_e32 v1, 16, v18
	v_and_b32_e32 v24, 0xffff0000, v18
	v_lshlrev_b32_e32 v56, 16, v19
	v_and_b32_e32 v57, 0xffff0000, v19
	v_lshlrev_b32_e32 v58, 16, v20
	v_and_b32_e32 v59, 0xffff0000, v20
	v_lshlrev_b32_e32 v60, 16, v21
	v_and_b32_e32 v61, 0xffff0000, v21
	v_lshlrev_b32_e32 v19, 16, v26
	v_mov_b32_e32 v20, v14
	v_mov_b32_e32 v21, v30
	v_and_b32_e32 v23, 0xffff0000, v26
	v_mov_b32_e32 v30, v15
	v_lshlrev_b32_e32 v15, 16, v27
	v_mov_b32_e32 v46, v16
	v_mov_b32_e32 v47, v32
	v_and_b32_e32 v27, 0xffff0000, v27
	v_mov_b32_e32 v32, v17
	v_lshlrev_b32_e32 v17, 16, v28
	v_mov_b32_e32 v50, v10
	v_mov_b32_e32 v51, v34
	v_mov_b32_e32 v54, v12
	v_mov_b32_e32 v55, v36
	v_mov_b32_e32 v36, v13
	v_lshlrev_b32_e32 v12, 16, v38
	v_and_b32_e32 v13, 0xffff0000, v38
	v_lshlrev_b32_e32 v38, 16, v39
	v_and_b32_e32 v39, 0xffff0000, v39
	v_lshlrev_b32_e32 v62, 16, v40
	v_and_b32_e32 v40, 0xffff0000, v40
	v_lshlrev_b32_e32 v63, 16, v41
	v_and_b32_e32 v41, 0xffff0000, v41
	v_lshlrev_b32_e32 v18, 16, v42
	v_and_b32_e32 v22, 0xffff0000, v42
	v_lshlrev_b32_e32 v14, 16, v43
	v_and_b32_e32 v26, 0xffff0000, v43
	v_lshlrev_b32_e32 v16, 16, v44
	v_and_b32_e32 v53, 0xffff0000, v28
	v_mov_b32_e32 v34, v11
	v_lshlrev_b32_e32 v11, 16, v29
	v_and_b32_e32 v29, 0xffff0000, v29
	v_and_b32_e32 v52, 0xffff0000, v44
	v_lshlrev_b32_e32 v10, 16, v45
	v_and_b32_e32 v28, 0xffff0000, v45
	v_fma_f32 v42, v6, v12, 0
	v_fma_f32 v43, v7, v13, 0
	v_fma_f32 v38, v8, v38, 0
	v_fma_f32 v39, v9, v39, 0
	v_fma_f32 v44, v2, v62, 0
	v_fma_f32 v40, v3, v40, 0
	v_fma_f32 v45, v4, v63, 0
	v_fma_f32 v41, v5, v41, 0
	v_pk_mul_f32 v[2:3], v[20:21], v[18:19]
	v_pk_mul_f32 v[4:5], v[30:31], v[22:23]
	v_pk_mul_f32 v[6:7], v[46:47], v[14:15]
	v_pk_mul_f32 v[8:9], v[32:33], v[26:27]
	v_pk_mul_f32 v[12:13], v[50:51], v[16:17]
	v_pk_mul_f32 v[14:15], v[34:35], v[52:53]
	v_pk_mul_f32 v[10:11], v[54:55], v[10:11]
	v_pk_mul_f32 v[16:17], v[36:37], v[28:29]
	v_add_f32_e32 v2, v2, v42
	v_add_f32_e32 v4, v4, v43
	v_add_f32_e32 v6, v6, v38
	v_add_f32_e32 v8, v8, v39
	v_add_f32_e32 v12, v44, v12
	v_add_f32_e32 v14, v40, v14
	v_add_f32_e32 v10, v45, v10
	v_add_f32_e32 v16, v41, v16
	v_add_f32_e32 v2, v2, v3
	v_add_f32_e32 v3, v4, v5
	v_add_f32_e32 v4, v6, v7
	v_add_f32_e32 v5, v8, v9
	v_add_f32_e32 v6, v12, v13
	v_add_f32_e32 v7, v14, v15
	v_add_f32_e32 v8, v10, v11
	v_add_f32_e32 v9, v16, v17
	v_mul_f32_e32 v1, v2, v1
	v_mul_f32_e32 v2, v3, v24
	v_mul_f32_e32 v3, v4, v56
	v_mul_f32_e32 v4, v5, v57
	v_mul_f32_e32 v5, v6, v58
	v_mul_f32_e32 v6, v7, v59
	v_mul_f32_e32 v7, v8, v60
	v_mul_f32_e32 v8, v9, v61
	v_cvt_pk_bf16_f32 v2, v1, v2
	v_cvt_pk_bf16_f32 v3, v3, v4
	v_cvt_pk_bf16_f32 v4, v5, v6
	v_cvt_pk_bf16_f32 v5, v7, v8
	global_store_dwordx4 v[48:49], v[2:5], off
	s_waitcnt vmcnt(1)
	v_pk_mul_f32 v[68:69], v[68:69], v[88:89] op_sel_hi:[1,0]
	v_pk_mul_f32 v[72:73], v[72:73], v[88:89] op_sel_hi:[1,0]
	v_pk_mul_f32 v[76:77], v[110:111], v[76:77] op_sel_hi:[0,1]
	v_pk_mul_f32 v[80:81], v[110:111], v[80:81] op_sel_hi:[0,1]
	v_pk_mul_f32 v[78:79], v[110:111], v[78:79] op_sel_hi:[0,1]
	v_pk_mul_f32 v[74:75], v[110:111], v[74:75] op_sel_hi:[0,1]
	v_pk_mul_f32 v[70:71], v[70:71], v[88:89] op_sel_hi:[1,0]
	v_pk_mul_f32 v[66:67], v[66:67], v[88:89] op_sel_hi:[1,0]
	v_lshlrev_b32_e32 v65, 16, v82
	v_and_b32_e32 v88, 0xffff0000, v82
	v_lshlrev_b32_e32 v120, 16, v83
	v_and_b32_e32 v121, 0xffff0000, v83
	v_lshlrev_b32_e32 v122, 16, v84
	v_and_b32_e32 v123, 0xffff0000, v84
	v_lshlrev_b32_e32 v124, 16, v85
	v_and_b32_e32 v125, 0xffff0000, v85
	v_lshlrev_b32_e32 v83, 16, v90
	v_mov_b32_e32 v84, v78
	v_mov_b32_e32 v85, v94
	v_and_b32_e32 v87, 0xffff0000, v90
	v_mov_b32_e32 v94, v79
	v_lshlrev_b32_e32 v79, 16, v91
	v_mov_b32_e32 v110, v80
	v_mov_b32_e32 v111, v96
	v_and_b32_e32 v91, 0xffff0000, v91
	v_mov_b32_e32 v96, v81
	v_lshlrev_b32_e32 v81, 16, v92
	v_mov_b32_e32 v114, v74
	v_mov_b32_e32 v115, v98
	v_mov_b32_e32 v118, v76
	v_mov_b32_e32 v119, v100
	v_mov_b32_e32 v100, v77
	v_lshlrev_b32_e32 v76, 16, v102
	v_and_b32_e32 v77, 0xffff0000, v102
	v_lshlrev_b32_e32 v102, 16, v103
	v_and_b32_e32 v103, 0xffff0000, v103
	v_lshlrev_b32_e32 v126, 16, v104
	v_and_b32_e32 v104, 0xffff0000, v104
	v_lshlrev_b32_e32 v127, 16, v105
	v_and_b32_e32 v105, 0xffff0000, v105
	v_lshlrev_b32_e32 v82, 16, v106
	v_and_b32_e32 v86, 0xffff0000, v106
	v_lshlrev_b32_e32 v78, 16, v107
	v_and_b32_e32 v90, 0xffff0000, v107
	v_lshlrev_b32_e32 v80, 16, v108
	v_and_b32_e32 v117, 0xffff0000, v92
	v_mov_b32_e32 v98, v75
	v_lshlrev_b32_e32 v75, 16, v93
	v_and_b32_e32 v93, 0xffff0000, v93
	v_and_b32_e32 v116, 0xffff0000, v108
	v_lshlrev_b32_e32 v74, 16, v109
	v_and_b32_e32 v92, 0xffff0000, v109
	v_fma_f32 v106, v70, v76, 0
	v_fma_f32 v107, v71, v77, 0
	v_fma_f32 v102, v72, v102, 0
	v_fma_f32 v103, v73, v103, 0
	v_fma_f32 v108, v66, v126, 0
	v_fma_f32 v104, v67, v104, 0
	v_fma_f32 v109, v68, v127, 0
	v_fma_f32 v105, v69, v105, 0
	v_pk_mul_f32 v[66:67], v[84:85], v[82:83]
	v_pk_mul_f32 v[68:69], v[94:95], v[86:87]
	v_pk_mul_f32 v[70:71], v[110:111], v[78:79]
	v_pk_mul_f32 v[72:73], v[96:97], v[90:91]
	v_pk_mul_f32 v[76:77], v[114:115], v[80:81]
	v_pk_mul_f32 v[78:79], v[98:99], v[116:117]
	v_pk_mul_f32 v[74:75], v[118:119], v[74:75]
	v_pk_mul_f32 v[80:81], v[100:101], v[92:93]
	v_add_f32_e32 v66, v66, v106
	v_add_f32_e32 v68, v68, v107
	v_add_f32_e32 v70, v70, v102
	v_add_f32_e32 v72, v72, v103
	v_add_f32_e32 v76, v108, v76
	v_add_f32_e32 v78, v104, v78
	v_add_f32_e32 v74, v109, v74
	v_add_f32_e32 v80, v105, v80
	v_add_f32_e32 v66, v66, v67
	v_add_f32_e32 v67, v68, v69
	v_add_f32_e32 v68, v70, v71
	v_add_f32_e32 v69, v72, v73
	v_add_f32_e32 v70, v76, v77
	v_add_f32_e32 v71, v78, v79
	v_add_f32_e32 v72, v74, v75
	v_add_f32_e32 v73, v80, v81
	v_mul_f32_e32 v65, v66, v65
	v_mul_f32_e32 v66, v67, v88
	v_mul_f32_e32 v67, v68, v120
	v_mul_f32_e32 v68, v69, v121
	v_mul_f32_e32 v69, v70, v122
	v_mul_f32_e32 v70, v71, v123
	v_mul_f32_e32 v71, v72, v124
	v_mul_f32_e32 v72, v73, v125
	v_cvt_pk_bf16_f32 v66, v65, v66
	v_cvt_pk_bf16_f32 v67, v67, v68
	v_cvt_pk_bf16_f32 v68, v69, v70
	v_cvt_pk_bf16_f32 v69, v71, v72
	global_store_dwordx4 v[112:113], v[66:69], off
	s_andn2_b64 exec, exec, s[10:11]
	s_cbranch_execnz .LBB0_290
	s_branch .LBB0_291
